# OUTPROJ layer-0 ctx-row tiles deferred past the barrier onto 32 workgroups (acquire counter in MLP1), MLP1 units rebalanced away from them
# speedup vs baseline: 1.0517x; 1.0112x over previous
; #define GEMMCALL if (0)
; __global__ void __launch_bounds__(NTHREADS, 2) mega(Params p) {
;     ...
;         {
;             pg8::Gemm g{MIX, (const bf16_t*)(ws + WS_WOUT) + (size_t)l * 1024 * KOUT, Mres, 1024, KOUT}; pg8::StaticOrder S; S.init(Mres, 1024, G, (int)blockIdx.x);
;             EpiResid2 E{xs, cs, p.out, XC, modl + 2 * 1024, A1, GS + (size_t)(l * 2 + 1) * 9 * 1024, RS + (size_t)(l * 2) * MT, l == 0 ? 1 : 0};
;             GEMMCALL pg8::gemm_phase<EpiResid2, pg8::StaticOrder, true, true>(lds, g, S, E);
.LBB0_543:
	s_or_b64 exec, exec, s[0:1]
	s_and_b64 s[0:1], s[64:65], exec
	s_movk_i32 s0, 0x88
	s_cselect_b32 s101, s0, 0x80
	s_movk_i32 s28, 0x80
	s_lshl_b32 s42, s28, 2
	s_cmp_lt_i32 s2, s42
	v_mov_b32_e32 v8, v220
	s_cselect_b64 s[0:1], -1, 0
	s_waitcnt lgkmcnt(0)
	s_barrier
	s_and_b64 vcc, exec, s[0:1]
	v_readfirstlane_b32 s4, v8
	s_cbranch_vccz .LBB0_545
	s_lshr_b32 s5, s28, 1
	v_readlane_b32 s6, v254, 62
	s_or_b32 s5, s5, s6
	v_readlane_b32 s6, v255, 30
	s_mul_i32 s5, s5, s6
	v_readlane_b32 s6, v255, 31
	s_add_i32 s5, s5, s6
	s_ashr_i32 s6, s5, 31
	s_lshr_b32 s6, s6, 27
	s_add_i32 s6, s5, s6
	s_ashr_i32 s7, s6, 5
	s_lshl_b32 s9, s7, 3
	s_sub_i32 s7, s28, s9
	s_min_i32 s10, s7, 8
	s_sext_i32_i8 s7, s10
	v_cvt_f32_i32_e32 v0, s7
	s_andn2_b32 s6, s6, 31
	s_sub_i32 s5, s5, s6
	v_cvt_f32_i32_e32 v1, s5
	v_rcp_iflag_f32_e32 v2, v0
	s_xor_b32 s6, s5, s7
	s_ashr_i32 s6, s6, 30
	s_or_b32 s8, s6, 1
	v_mul_f32_e32 v2, v1, v2
	v_trunc_f32_e32 v2, v2
	v_fma_f32 v1, -v2, v0, v1
	v_cvt_i32_f32_e32 v2, v2
	v_cmp_ge_f32_e64 s[6:7], |v1|, |v0|
	s_and_b64 s[6:7], s[6:7], exec
	s_cselect_b32 s6, s8, 0
	v_readfirstlane_b32 s7, v2
	s_add_i32 s6, s7, s6
	s_sext_i32_i8 s8, s6
	s_mul_i32 s6, s6, s10
	s_sub_i32 s5, s5, s6
	s_sext_i32_i8 s5, s5
	s_add_i32 s36, s9, s5

;     __device__ bool next(int i, pg8::Unit& u) const { if (i != 0 || !has) return false; u.pm = pm; u.pn = pn; return true; }
;     __host__ __device__ bool next(int i, Unit& u) const {
;         const long L = (long)i * G + c; if (L >= nwg) return false;
;         int wgid = (int)L; { const int q = nwg / NXCD, r = nwg % NXCD, xcd = wgid % NXCD, off = wgid / NXCD; wgid = (xcd < r ? xcd * (q + 1) : r * (q + 1) + (xcd - r) * q) + off; }
;         const int nig = WGM * nN, gid = wgid / nig, fm = gid * WGM, gsz = (nM - fm) < WGM ? (nM - fm) : WGM;
;         u.pm = fm + ((wgid % nig) % gsz); u.pn = (wgid % nig) / gsz; return true;
;     }
; template <class Epi, class Sched, bool ALIGN_EPI = false, bool SP2 = false>
; __device__ __forceinline__ void gemm_phase(PG8_LAS unsigned char* lds, const Gemm g, const Sched& S, const Epi& E) {
;     ...
;         const bool has_next = S.next(ui + 1, nxt);
;         const char* nA = has_next ? (const char*)g.A + (size_t)nxt.pm * tstep : cA; const char* nB = has_next ? (const char*)g.Bt + (size_t)nxt.pn * tstep : cB;
.LBB0_551:
	s_add_i32 s61, s61, 1
	s_mul_i32 s9, s61, s33
	s_mul_hi_u32 s12, s61, s90
	s_add_i32 s9, s12, s9
	s_mul_i32 s12, s61, s90
	s_add_u32 s12, s12, s2
	s_addc_u32 s13, s9, s85
	s_waitcnt lgkmcnt(0)
	v_mov_b64_e32 v[0:1], s[42:43]
	v_cmp_ge_i64_e32 vcc, s[12:13], v[0:1]
	v_cmp_lt_i64_e64 s[40:41], s[12:13], v[0:1]
	s_cmpk_lg_u32 s101, 0x88
	s_cbranch_scc1 .Lop_norm
	s_cmp_lg_u32 s61, 2
	s_cbranch_scc1 .Lop_norm
	s_sub_u32 s12, s2, 0x80
	s_cmp_lt_u32 s12, 32
	s_cselect_b64 s[40:41], -1, 0
	s_and_b32 s48, s12, 7
	s_add_i32 s48, s48, 0x80
	s_lshr_b32 s46, s12, 3
	s_branch .LBB0_553
.Lop_norm:
	s_cbranch_vccnz .LBB0_553
	s_ashr_i32 s9, s12, 31
	s_lshr_b32 s9, s9, 29
	s_add_i32 s9, s12, s9
	s_ashr_i32 s13, s9, 3
	s_and_b32 s9, s9, -8
	s_sub_i32 s9, s12, s9
	s_lshr_b32 s12, s9, 31
	s_or_b32 s12, s92, s12
	s_mul_i32 s9, s12, s9
	s_add_i32 s9, s9, s13
	s_ashr_i32 s12, s9, 31
	s_lshr_b32 s12, s12, 27
	s_add_i32 s12, s9, s12
	s_ashr_i32 s13, s12, 5
	s_lshl_b32 s13, s13, 3
	s_sub_i32 s37, s28, s13
	s_min_i32 s37, s37, 8
	s_abs_i32 s46, s37
	v_cvt_f32_u32_e32 v0, s46
	s_sub_i32 s48, 0, s46
	s_andn2_b32 s12, s12, 31
	s_sub_i32 s9, s9, s12
	v_rcp_iflag_f32_e32 v0, v0
	s_abs_i32 s12, s9
	s_xor_b32 s47, s9, s37
	s_ashr_i32 s47, s47, 31
	v_mul_f32_e32 v0, 0x4f7ffffe, v0
	v_cvt_u32_f32_e32 v0, v0
	s_nop 0
	v_readfirstlane_b32 s49, v0
	s_mul_i32 s48, s48, s49
	s_mul_hi_u32 s48, s49, s48
	s_add_i32 s49, s49, s48
	s_mul_hi_u32 s48, s12, s49
	s_mul_i32 s49, s48, s46
	s_sub_i32 s12, s12, s49
	s_add_i32 s54, s48, 1
	s_sub_i32 s49, s12, s46
	s_cmp_ge_u32 s12, s46
	s_cselect_b32 s48, s54, s48
	s_cselect_b32 s12, s49, s12
	s_add_i32 s49, s48, 1
	s_cmp_ge_u32 s12, s46
	s_cselect_b32 s12, s49, s48
	s_xor_b32 s12, s12, s47
	s_sub_i32 s46, s12, s47
	s_mul_i32 s12, s46, s37
	s_sub_i32 s9, s9, s12
	s_add_i32 s48, s9, s13

; #define PG8_BAR __builtin_amdgcn_s_barrier()
; __device__ __forceinline__ unsigned xb_add(unsigned* p, unsigned v) { return __hip_atomic_fetch_add(p, v, __ATOMIC_RELAXED, __HIP_MEMORY_SCOPE_AGENT); }
; template <class Epi, class Sched, bool ALIGN_EPI = false, bool SP2 = false>
; __device__ __forceinline__ void gemm_phase(PG8_LAS unsigned char* lds, const Gemm g, const Sched& S, const Epi& E) {
;     ...
;         if constexpr (ALIGN_EPI) { if (wr == 0) PG8_BAR; }
;         if constexpr (!Epi::AFTER_DRAIN) { E(acc, cur, wr, wc, fr, fq); S.done(cur); }
;         if (!has_next) break;
; __device__ __forceinline__ void xcd_barrier(const XcdBarrier& b) {
;     asm volatile("s_waitcnt vmcnt(0)" ::: "memory");
;     __syncthreads();
;     if (threadIdx.x == 0) {
;         unsigned* bar = b.bar;
;         __builtin_amdgcn_s_waitcnt(0);
;         unsigned nloc = b.st[0], nx = b.st[1];
;         if (nloc == 0u) { xcd_barrier_complete(bar, b.x, nloc, nx); b.st[0] = nloc; b.st[1] = nx; }
;         const unsigned old = xb_add(&bar[XB_XSUB(b.x)], 1u);
.LBB0_573:
	s_or_b64 exec, exec, s[6:7]
	s_cmpk_lg_u32 s101, 0x88
	s_cbranch_scc1 .Lop_nobar
	s_cmp_lg_u32 s61, 2
	s_cbranch_scc1 .Lop_nobar
	s_and_b64 s[6:7], s[40:41], exec
	s_cbranch_scc0 .Lop_nobar
	s_waitcnt vmcnt(0) lgkmcnt(0)
	s_barrier
	s_add_i32 s98, s98, 1
	s_mov_b64 s[12:13], exec
	v_readlane_b32 s6, v252, 0
	v_readlane_b32 s7, v252, 1
	s_and_b64 s[6:7], s[12:13], s[6:7]
	s_mov_b64 exec, s[6:7]
	s_cbranch_execz .Lop_barx
	s_add_u32 s10, s88, 0x9000
	s_addc_u32 s11, s89, 0
	s_cmp_lg_u32 s100, 0
	s_cbranch_scc1 .Lxb_have_o
	s_add_u32 s8, s88, 0x1400
	s_addc_u32 s9, s89, 0
.Lxb_census_o:
	v_mov_b32_e32 v0, 0
	global_load_dword v1, v0, s[8:9] sc1
	global_load_dword v2, v0, s[8:9] offset:256 sc1
	global_load_dword v3, v0, s[8:9] offset:512 sc1
	global_load_dword v4, v0, s[8:9] offset:768 sc1
	global_load_dword v5, v0, s[8:9] offset:1024 sc1
	global_load_dword v6, v0, s[8:9] offset:1280 sc1
	global_load_dword v7, v0, s[8:9] offset:1536 sc1
	global_load_dword v8, v0, s[8:9] offset:1792 sc1
	global_load_dword v9, v0, s[8:9] offset:2048 sc1
	global_load_dword v10, v0, s[8:9] offset:2304 sc1
	global_load_dword v11, v0, s[8:9] offset:2560 sc1
	global_load_dword v12, v0, s[8:9] offset:2816 sc1
	global_load_dword v13, v0, s[8:9] offset:3072 sc1
	global_load_dword v14, v0, s[8:9] offset:3328 sc1
	global_load_dword v15, v0, s[8:9] offset:3584 sc1
	global_load_dword v16, v0, s[8:9] offset:3840 sc1
	s_waitcnt vmcnt(0)
	v_add3_u32 v0, v1, v2, v3
	v_add3_u32 v0, v0, v4, v5
	v_add3_u32 v0, v0, v6, v7
	v_add3_u32 v0, v0, v8, v9
	v_add3_u32 v0, v0, v10, v11
	v_add3_u32 v0, v0, v12, v13
	v_add3_u32 v0, v0, v14, v15
	v_add_u32_e32 v0, v0, v16
	s_nop 0
	v_readfirstlane_b32 s36, v0
	s_nop 3
	s_cmp_eq_u32 s36, s90
	s_cbranch_scc1 .Lxb_cdone_o
	s_sleep 2
	s_branch .Lxb_census_o

; __device__ __forceinline__ unsigned xb_ld(unsigned* p)              { return __hip_atomic_load(p, __ATOMIC_RELAXED, __HIP_MEMORY_SCOPE_AGENT); }
; __device__ __forceinline__ unsigned xb_add(unsigned* p, unsigned v) { return __hip_atomic_fetch_add(p, v, __ATOMIC_RELAXED, __HIP_MEMORY_SCOPE_AGENT); }
; #define XB_SPIN(cond, bar) do { unsigned _sp = 0; while (cond) { __builtin_amdgcn_s_sleep(1); \
;     if ((++_sp & 255u) == 0u) { if (xb_ld(&(bar)[XB_TMO])) break; if (_sp > XB_SPIN_CAP) { atomicAdd(&(bar)[XB_TMO], 1u); break; } } } } while (0)
; __device__ __forceinline__ void xcd_barrier(const XcdBarrier& b) {
;     ...
;         const unsigned old = xb_add(&bar[XB_XSUB(b.x)], 1u);
;         const unsigned gen = old / nloc;
;         if (old + 1u == (gen + 1u) * nloc) {
;             __builtin_amdgcn_fence(__ATOMIC_RELEASE, "agent");
;             asm volatile("s_waitcnt vmcnt(0)" ::: "memory");
;             const unsigned og = xb_add(&bar[XB_TOP], 1u);
;             const unsigned tg = og / nx;
;             if (og + 1u == (tg + 1u) * nx) xb_add(&bar[XB_TOPGEN], 1u);
;             else XB_SPIN(xb_ld(&bar[XB_TOPGEN]) == tg, bar);
;             __builtin_amdgcn_fence(__ATOMIC_ACQUIRE, "agent");
;             xb_add(&bar[XB_XGEN(b.x)], 1u);
;             asm volatile("s_waitcnt vmcnt(0)" ::: "memory");
.Lxb_have_o:
	s_lshl_b32 s6, s99, 8
	v_mov_b32_e32 v0, s6
	v_mov_b32_e32 v1, 1
	global_atomic_add v2, v0, v1, s[10:11] sc0
	s_mul_i32 s7, s98, s100
	s_waitcnt vmcnt(0)
	v_readfirstlane_b32 s36, v2
	s_nop 3
	s_add_i32 s36, s36, 1
	s_cmp_lg_u32 s36, s7
	s_cbranch_scc1 .Lxb_poll_o
	buffer_wbl2 sc1
	s_waitcnt vmcnt(0)
	v_mov_b32_e32 v3, 0x1000
	v_mov_b32_e32 v4, s100
	global_atomic_add v2, v3, v4, s[10:11] sc0
	s_mul_i32 s7, s98, s90
	s_waitcnt vmcnt(0)
	v_readfirstlane_b32 s36, v2
	s_nop 3
	s_add_i32 s36, s36, s100
	s_cmp_lg_u32 s36, s7
	s_cbranch_scc1 .Lxb_poll_o
	v_mov_b32_e32 v3, 0
	v_mov_b32_e32 v4, s98
	s_add_u32 s8, s10, 0x1100
	s_addc_u32 s9, s11, 0
	global_store_dword v3, v4, s[8:9] sc0 sc1
	global_store_dword v3, v4, s[8:9] offset:256 sc0 sc1
	global_store_dword v3, v4, s[8:9] offset:512 sc0 sc1
	global_store_dword v3, v4, s[8:9] offset:768 sc0 sc1
	global_store_dword v3, v4, s[8:9] offset:1024 sc0 sc1
	global_store_dword v3, v4, s[8:9] offset:1280 sc0 sc1
	global_store_dword v3, v4, s[8:9] offset:1536 sc0 sc1
	global_store_dword v3, v4, s[8:9] offset:1792 sc0 sc1
	global_store_dword v3, v4, s[8:9] offset:2048 sc0 sc1
	global_store_dword v3, v4, s[8:9] offset:2304 sc0 sc1
	global_store_dword v3, v4, s[8:9] offset:2560 sc0 sc1
	global_store_dword v3, v4, s[8:9] offset:2816 sc0 sc1
	global_store_dword v3, v4, s[8:9] offset:3072 sc0 sc1
	global_store_dword v3, v4, s[8:9] offset:3328 sc0 sc1
	global_store_dword v3, v4, s[8:9] offset:3584 sc0 sc1
	global_store_dword v3, v4, s[8:9] offset:3840 sc0 sc1
	s_waitcnt vmcnt(0)

; #define PG8_BAR __builtin_amdgcn_s_barrier()
; template <class Epi, class Sched, bool ALIGN_EPI = false, bool SP2 = false>
; __device__ __forceinline__ void gemm_phase(PG8_LAS unsigned char* lds, const Gemm g, const Sched& S, const Epi& E) {
;     ...
;         if constexpr (ALIGN_EPI) { if (wr == 0) PG8_BAR; }
;         if constexpr (!Epi::AFTER_DRAIN) { E(acc, cur, wr, wc, fr, fq); S.done(cur); }
;         if (!has_next) break;
; #pragma unroll
;         for (int a = 0; a < 2; ++a)
; #pragma unroll
;             for (int b = 0; b < 2; ++b)
; #pragma unroll
;                 for (int m = 0; m < 4; ++m)
; #pragma unroll
;                     for (int n = 0; n < 2; ++n) acc[a][b][m][n] = (f32x4){0.f, 0.f, 0.f, 0.f};
;         cur = nxt; cA = nA; cB = nB; ++ui;
;         if constexpr (ALIGN_EPI) { if (wr == 1) PG8_BAR; }
.Lop_barx:
	s_or_b64 exec, exec, s[12:13]
	s_barrier
.Lop_nobar:
	s_andn2_b64 vcc, exec, s[40:41]
	s_mov_b64 s[6:7], -1
	s_cbranch_vccnz .LBB0_550
	s_andn2_b64 vcc, exec, s[0:1]
	s_cbranch_vccnz .LBB0_549
	s_barrier
	s_branch .LBB0_549

; #define GEMMCALL if (0)
; #define GBAR() do { for (int rep = 0; rep < REP_BAR; ++rep) xcd_barrier(xb); } while (0)
; __global__ void __launch_bounds__(NTHREADS, 2) mega(Params p) {
;     ...
;             GEMMCALL pg8::gemm_phase<EpiResid2, pg8::StaticOrder, true, true>(lds, g, S, E);
;         }
;         GBAR();
.LBB0_577:
	s_mov_b32 s28, s101
	s_mov_b32 s101, 0
	s_cmpk_lg_u32 s28, 0x88
	s_cbranch_scc1 .Lop_xbar
	s_sub_u32 s6, s2, 0x80
	s_cmp_lt_u32 s6, 32
	s_cbranch_scc0 .Lop_xbar
	s_waitcnt vmcnt(0) lgkmcnt(0)
	s_barrier
	s_mov_b64 s[0:1], exec
	v_readlane_b32 s6, v252, 0
	v_readlane_b32 s7, v252, 1
	s_and_b64 s[6:7], s[0:1], s[6:7]
	s_mov_b64 exec, s[6:7]
	s_cbranch_execz .LBB0_629
	buffer_wbl2 sc1
	s_waitcnt vmcnt(0)
	s_add_u32 s10, s88, 0xc000
	s_addc_u32 s11, s89, 0
	v_mov_b32_e32 v0, 0
	v_mov_b32_e32 v1, 1
	global_atomic_add v0, v1, s[10:11]
	s_waitcnt vmcnt(0)
	s_branch .LBB0_629

;     __device__ bool next(int i, pg8::Unit& u) const { if (i != 0 || !has) return false; u.pm = pm; u.pn = pn; return true; }
;     __host__ __device__ bool next(int i, Unit& u) const {
;         const long L = (long)i * G + c; if (L >= nwg) return false;
;         int wgid = (int)L; { const int q = nwg / NXCD, r = nwg % NXCD, xcd = wgid % NXCD, off = wgid / NXCD; wgid = (xcd < r ? xcd * (q + 1) : r * (q + 1) + (xcd - r) * q) + off; }
;         const int nig = WGM * nN, gid = wgid / nig, fm = gid * WGM, gsz = (nM - fm) < WGM ? (nM - fm) : WGM;
;         u.pm = fm + ((wgid % nig) % gsz); u.pn = (wgid % nig) / gsz; return true;
;     }
; template <class Epi, class Sched, bool ALIGN_EPI = false, bool SP2 = false>
; __device__ __forceinline__ void gemm_phase(PG8_LAS unsigned char* lds, const Gemm g, const Sched& S, const Epi& E) {
;     ...
;         const bool has_next = S.next(ui + 1, nxt);
;         const char* nA = has_next ? (const char*)g.A + (size_t)nxt.pm * tstep : cA; const char* nB = has_next ? (const char*)g.Bt + (size_t)nxt.pn * tstep : cB;
;         for (int t = 0; t < nt; t += 2) {
;             const bool last = (t == nt - 2);
;             const char* a1 = cA + (size_t)(t + 1) * kstep;
;             const char* a2 = last ? nA : cA + (size_t)(t + 2) * kstep; const char* b2 = last ? nB : cB + (size_t)(t + 2) * kstep;
;             const char* a3 = a2 + kstep; const char* b3 = b2 + kstep;
;             if (last && has_next) S.a_ready(nxt);
.LBB0_635:
	s_add_i32 s66, s66, 1
	s_mul_i32 s0, s66, s33
	s_mul_hi_u32 s1, s66, s90
	s_add_i32 s1, s1, s0
	s_mul_i32 s0, s66, s90
	s_add_u32 s40, s0, s2
	s_addc_u32 s41, s1, s85
	s_cmpk_lg_u32 s28, 0x88
	s_cbranch_scc1 .Lm1_map
	s_cmp_lg_u32 s66, 7
	s_cbranch_scc1 .Lm1_r8
	s_sub_u32 s0, s2, 0x80
	s_cmp_lt_u32 s0, 32
	s_cbranch_scc0 .Lm1_map
	s_mov_b32 s40, 0x7fffffff
	s_mov_b32 s41, 0
	s_branch .Lm1_map
.Lm1_r8:
	s_cmp_lg_u32 s66, 8
	s_cbranch_scc1 .Lm1_map
	s_sub_u32 s0, s2, 0xa0
	s_cmp_lt_u32 s0, 32
	s_cbranch_scc0 .Lm1_map
	s_add_u32 s40, s2, 0x6e0
	s_mov_b32 s41, 0
.Lm1_map:
	v_mov_b64_e32 v[0:1], s[76:77]
	v_cmp_ge_i64_e32 vcc, s[40:41], v[0:1]
	v_cmp_lt_i64_e64 s[0:1], s[40:41], v[0:1]
	s_cbranch_vccnz .LBB0_637
	s_ashr_i32 s8, s40, 31
	s_lshr_b32 s8, s8, 29
	s_add_i32 s8, s40, s8
	s_ashr_i32 s9, s8, 3
	s_and_b32 s8, s8, -8
	s_sub_i32 s8, s40, s8
	s_cmp_lt_i32 s8, 0
	s_cselect_b32 s11, s52, s43
	s_mul_i32 s8, s11, s8
	s_add_i32 s8, s8, s9
	s_ashr_i32 s9, s8, 31
	s_lshr_b32 s9, s9, 25
	s_add_i32 s9, s8, s9
	s_ashr_i32 s11, s9, 7
	s_lshl_b32 s11, s11, 3
	s_sub_i32 s36, s28, s11
	s_min_i32 s36, s36, 8
	s_abs_i32 s37, s36
	v_cvt_f32_u32_e32 v0, s37
	s_sub_i32 s41, 0, s37
	s_and_b32 s9, s9, 0xffffff80
	s_sub_i32 s9, s8, s9
	v_rcp_iflag_f32_e32 v0, v0
	s_abs_i32 s8, s9
	s_xor_b32 s40, s9, s36
	s_ashr_i32 s40, s40, 31
	v_mul_f32_e32 v0, 0x4f7ffffe, v0
	v_cvt_u32_f32_e32 v0, v0
	s_nop 0
	v_readfirstlane_b32 s46, v0
	s_mul_i32 s41, s41, s46
	s_mul_hi_u32 s41, s46, s41
	s_add_i32 s46, s46, s41
	s_mul_hi_u32 s41, s8, s46
	s_mul_i32 s46, s41, s37
	s_sub_i32 s8, s8, s46
	s_add_i32 s47, s41, 1
	s_sub_i32 s46, s8, s37
	s_cmp_ge_u32 s8, s37
	s_cselect_b32 s41, s47, s41
	s_cselect_b32 s8, s46, s8
	s_add_i32 s46, s41, 1
	s_cmp_ge_u32 s8, s37
	s_cselect_b32 s8, s46, s41
	s_xor_b32 s8, s8, s40
	s_sub_i32 s8, s8, s40
	s_mul_i32 s36, s8, s36
	s_sub_i32 s9, s9, s36
	s_add_i32 s36, s9, s11
.LBB0_637:
	s_cmpk_lg_u32 s28, 0x88
	s_cbranch_scc1 .Lm1_noacq
	s_cmp_lg_u32 s101, 0
	s_cbranch_scc1 .Lm1_noacq
	s_and_b64 s[46:47], s[0:1], exec
	s_cbranch_scc0 .Lm1_noacq
	s_cmpk_lt_i32 s36, 0x80
	s_cbranch_scc1 .Lm1_noacq
	s_add_u32 s46, s88, 0xc000
	s_addc_u32 s47, s89, 0
	v_mov_b32_e32 v0, 0
.Lm1_spin:
	global_load_dword v1, v0, s[46:47] sc1
	s_waitcnt vmcnt(0)
	v_readfirstlane_b32 s40, v1
	s_nop 3
	s_cmp_ge_u32 s40, 32
	s_cbranch_scc1 .Lm1_acq
	s_sleep 2
	s_branch .Lm1_spin
.Lm1_acq:
	buffer_inv sc1
	s_mov_b32 s101, 1
